# v43 + FoX in-loop: per-tile K/V/F pointer math (two 64-bit multiplies + selects) replaced by per-unit bases plus one scalar-offset add each
# baseline (speedup 1.0000x reference)
; template <int TY> __device__ __forceinline__ void attn_unit(LAS unsigned char* lds, const AttnArgs& a, int b, int h, int qt, int wave_s) {
;     ...
;     const int ki = tid >> 3, kc = tid & 7, ki2 = tid >> 2, kc2 = tid & 3;
;     const int kwoff = ((ki >> 4) * NDS + (kc >> 2)) * 1024 + ((((ki & 15) * 64) + (kc & 3) * 16) ^ (((ki & 15) >> 3) << 5));
;     const int kwoff2 = (((ki2 & 63) >> 4) * NDS + (NDS - 1)) * 1024 + ((((ki2 & 15) * 64) + kc2 * 16) ^ (((ki2 & 15) >> 3) << 5));
;     u32x4 kregA, vregA, kreg2A = {0u, 0u, 0u, 0u}; float fregA = 0.f;
;     u32x4 kregB = {0u, 0u, 0u, 0u}, vregB = {0u, 0u, 0u, 0u}, kreg2B = {0u, 0u, 0u, 0u}; float fregB = 0.f;
.LBB0_758:
	s_and_b64 vcc, exec, s[6:7]
	s_cbranch_vccnz .LBB0_790
	s_add_i32 s21, s17, 31
	s_add_u32 s6, s82, s8
	s_addc_u32 s7, s83, 0
	s_add_i32 s8, s62, s12
	v_add_u32_e32 v1, s8, v168
	v_or_b32_e32 v144, s19, v190
	v_add_u32_e32 v242, s19, v169
	v_mad_i64_i32 v[238:239], s[100:101], v242, s40, v[164:165]
	v_mad_i64_i32 v[236:237], s[100:101], v242, s40, v[162:163]
	v_mov_b32_e32 v240, v144
	v_ashrrev_i32_e32 v241, 31, v144
	v_lshlrev_b64 v[240:241], 5, v[240:241]
	v_lshl_add_u64 v[240:241], s[6:7], 0, v[240:241]
	v_sub_u32_e32 v145, v1, v176
	s_mov_b32 s22, 5
	s_movk_i32 s23, 0xff
	s_branch .LBB0_763

; #define LAS __attribute__((address_space(3)))
; template <int TY> __device__ __forceinline__ void attn_unit(LAS unsigned char* lds, const AttnArgs& a, int b, int h, int qt, int wave_s) {
;     ...
;         { const int Jn = J + 2 <= J1 ? J + 2 : J1; if (hf == 0) ATT_LOAD(A, Jn); else ATT_LOAD(B, Jn); }
;         const bool skip = (64 * J > ewhi) || (TY == 0 && 64 * J + 63 + 127 < ewlo);
;         if (!skip) {
;         int lim[2]; f32x4 cinit[2];
; #pragma unroll
;         for (int qb = 0; qb < 2; ++qb) {
;             lim[qb] = eq[qb] - 64 * J - 4 * fq;
;             const float c0 = TY == 0 ? -(mrun[qb] + slope2 * (float)lim[qb]) : -mrun[qb];
;             cinit[qb] = (f32x4){c0, c0, c0, c0};
;         }
;         f32x4 s[2][4];
;         bf16x8 kfr[4][NDS];
; #pragma unroll
;         for (int kb = 0; kb < 4; ++kb)
; #pragma unroll
;             for (int ds = 0; ds < NDS; ++ds) kfr[kb][ds] = *(const LAS bf16x8*)(sb + koff + (kb * NDS + ds) * 1024);
; #pragma unroll
;         for (int kb = 0; kb < 4; ++kb) {
; #pragma unroll
;             for (int ds = 0; ds < NDS; ++ds) {
;                 s[0][kb] = __builtin_amdgcn_mfma_f32_16x16x32_bf16(kfr[kb][ds], qf[0][ds], ds == 0 ? cinit[0] : s[0][kb], 0, 0, 0);
;                 s[1][kb] = __builtin_amdgcn_mfma_f32_16x16x32_bf16(kfr[kb][ds], qf[1][ds], ds == 0 ? cinit[1] : s[1][kb], 0, 0, 0);
;             }
;         }
;         bf16x8 vf[4][2];
; #pragma unroll
;         for (int db = 0; db < 4; ++db)
; #pragma unroll
;             for (int G = 0; G < 2; ++G) {
;                 LAS unsigned char* vp = sb + voff + (32 * G * VSTR + 16 * db) * 2;
;                 const v4i16_t lo = __builtin_amdgcn_ds_read_tr16_b64_v4i16((LAS v4i16_t*)vp), hi = __builtin_amdgcn_ds_read_tr16_b64_v4i16((LAS v4i16_t*)(vp + 16 * VSTR * 2));
;                 vf[db][G] = (bf16x8){lo[0], lo[1], lo[2], lo[3], hi[0], hi[1], hi[2], hi[3]};
;             }
;         if (TY == 1) {
; #pragma unroll
;             for (int kb = 0; kb < 4; ++kb) {
;                 const f32x4 fk = *(const LAS f32x4*)(sb + KBYTES + VBYTES + (16 * kb + 4 * fq) * 4);
;                 s[0][kb] -= fk; s[1][kb] -= fk;
;             }
;         }
.LBB0_763:
	s_add_i32 s24, s22, -3
	s_cmp_le_u32 s24, s20
	s_cselect_b64 s[8:9], -1, 0
	s_and_b64 vcc, exec, s[8:9]
	s_cbranch_vccz .LBB0_777
	s_add_i32 s10, s22, -1
	s_min_i32 s10, s10, s20
	s_lshl_b32 s25, s10, 6
	s_mul_i32 s100, s25, s40
	s_mov_b32 s101, 0
	v_lshl_add_u64 v[10:11], s[100:101], 0, v[236:237]
	v_lshl_add_u64 v[12:13], s[100:101], 0, v[238:239]
	global_load_dwordx4 v[70:73], v[10:11], off
	global_load_dwordx4 v[74:77], v[12:13], off
	s_lshl_b32 s100, s25, 5
	v_lshl_add_u64 v[10:11], s[100:101], 0, v[240:241]
	global_load_dword v189, v[10:11], off
	s_add_i32 s10, s23, 0xffffff81
	s_cmp_gt_i32 s10, s21
	s_cbranch_scc1 .LBB0_772
	v_xor_b32_e32 v10, 0x80000000, v167
	v_xor_b32_e32 v14, 0x80000000, v166
	v_mov_b32_e32 v11, v10
	v_mov_b32_e32 v12, v10
	v_mov_b32_e32 v13, v10
	v_mov_b32_e32 v15, v14
	v_mov_b32_e32 v16, v14
	v_mov_b32_e32 v17, v14
	ds_read_b128 v[90:93], v186
	ds_read_b128 v[94:97], v186 offset:1024
	ds_read_b128 v[98:101], v186 offset:2048
	ds_read_b128 v[102:105], v186 offset:3072
	ds_read_b128 v[106:109], v186 offset:4096
	ds_read_b128 v[110:113], v186 offset:5120
	ds_read_b128 v[114:117], v186 offset:6144
	ds_read_b128 v[118:121], v186 offset:7168
	s_waitcnt lgkmcnt(7)
	v_mfma_f32_16x16x32_bf16 v[122:125], v[90:93], v[38:41], v[10:13]
	s_sub_i32 s10, s23, 64
	s_cmp_gt_i32 s10, s17
	s_mov_b64 s[10:11], -1
	v_mfma_f32_16x16x32_bf16 v[90:93], v[90:93], v[46:49], v[14:17]
	s_waitcnt lgkmcnt(6)
	v_mfma_f32_16x16x32_bf16 v[126:129], v[94:97], v[42:45], v[122:125]
	v_mfma_f32_16x16x32_bf16 v[130:133], v[94:97], v[50:53], v[90:93]
	s_waitcnt lgkmcnt(5)
	v_mfma_f32_16x16x32_bf16 v[90:93], v[98:101], v[38:41], v[10:13]
	v_mfma_f32_16x16x32_bf16 v[94:97], v[98:101], v[46:49], v[14:17]
	s_waitcnt lgkmcnt(4)
	v_mfma_f32_16x16x32_bf16 v[146:149], v[102:105], v[42:45], v[90:93]
	v_mfma_f32_16x16x32_bf16 v[190:193], v[102:105], v[50:53], v[94:97]
	s_waitcnt lgkmcnt(3)
	v_mfma_f32_16x16x32_bf16 v[90:93], v[106:109], v[38:41], v[10:13]
	v_mfma_f32_16x16x32_bf16 v[94:97], v[106:109], v[46:49], v[14:17]
	s_waitcnt lgkmcnt(1)
	v_mfma_f32_16x16x32_bf16 v[10:13], v[114:117], v[38:41], v[10:13]
	v_mfma_f32_16x16x32_bf16 v[14:17], v[114:117], v[46:49], v[14:17]
	v_mfma_f32_16x16x32_bf16 v[194:197], v[110:113], v[42:45], v[90:93]
	v_mfma_f32_16x16x32_bf16 v[122:125], v[110:113], v[50:53], v[94:97]
	s_waitcnt lgkmcnt(0)
	v_mfma_f32_16x16x32_bf16 v[140:143], v[118:121], v[42:45], v[10:13]
	v_mfma_f32_16x16x32_bf16 v[136:139], v[118:121], v[50:53], v[14:17]
	ds_read_b64_tr_b16 v[94:95], v187 offset:8192
	s_nop 0
	ds_read_b64_tr_b16 v[10:11], v187 offset:8224
	ds_read_b64_tr_b16 v[96:97], v187 offset:10752
	ds_read_b64_tr_b16 v[90:91], v187 offset:13312
	ds_read_b64_tr_b16 v[92:93], v187 offset:15872
	ds_read_b64_tr_b16 v[12:13], v187 offset:10784
	ds_read_b64_tr_b16 v[14:15], v187 offset:13344
	ds_read_b64_tr_b16 v[16:17], v187 offset:15904
	ds_read_b64_tr_b16 v[102:103], v187 offset:8256
	ds_read_b64_tr_b16 v[104:105], v187 offset:10816
	ds_read_b64_tr_b16 v[98:99], v187 offset:13376
	ds_read_b64_tr_b16 v[100:101], v187 offset:15936
	ds_read_b64_tr_b16 v[106:107], v187 offset:8288
	ds_read_b64_tr_b16 v[108:109], v187 offset:10848
	ds_read_b64_tr_b16 v[110:111], v187 offset:13408
	ds_read_b64_tr_b16 v[112:113], v187 offset:15968
	ds_read_b128 v[216:219], v188 offset:18432
	ds_read_b128 v[220:223], v188 offset:18496
	ds_read_b128 v[224:227], v188 offset:18560
	ds_read_b128 v[228:231], v188 offset:18624
	s_waitcnt lgkmcnt(0)
	s_cselect_b32 s99, 1, 0
	s_bitcmp1_b32 s41, 8
	s_cbranch_scc1 .Lfx_h0p1_end
	s_cmp_ge_u32 s24, s20
	s_cbranch_scc1 .Lfx_h0p1_bar
	s_waitcnt vmcnt(5)
	ds_write_b128 v182, v[62:65] offset:18688
	s_waitcnt vmcnt(4)
	ds_write_b128 v183, v[66:69] offset:26880
	s_and_saveexec_b64 s[100:101], s[4:5]
	s_cbranch_execz .Lfx_h0p1_w
	s_waitcnt vmcnt(3)
	ds_write_b32 v184, v185 offset:37120

; #define LAS __attribute__((address_space(3)))
; template <int TY> __device__ __forceinline__ void attn_unit(LAS unsigned char* lds, const AttnArgs& a, int b, int h, int qt, int wave_s) {
;     ...
;         { const int Jn = J + 2 <= J1 ? J + 2 : J1; if (hf == 0) ATT_LOAD(A, Jn); else ATT_LOAD(B, Jn); }
;         const bool skip = (64 * J > ewhi) || (TY == 0 && 64 * J + 63 + 127 < ewlo);
;         if (!skip) {
;         int lim[2]; f32x4 cinit[2];
; #pragma unroll
;         for (int qb = 0; qb < 2; ++qb) {
;             lim[qb] = eq[qb] - 64 * J - 4 * fq;
;             const float c0 = TY == 0 ? -(mrun[qb] + slope2 * (float)lim[qb]) : -mrun[qb];
;             cinit[qb] = (f32x4){c0, c0, c0, c0};
;         }
;         f32x4 s[2][4];
;         bf16x8 kfr[4][NDS];
; #pragma unroll
;         for (int kb = 0; kb < 4; ++kb)
; #pragma unroll
;             for (int ds = 0; ds < NDS; ++ds) kfr[kb][ds] = *(const LAS bf16x8*)(sb + koff + (kb * NDS + ds) * 1024);
; #pragma unroll
;         for (int kb = 0; kb < 4; ++kb) {
; #pragma unroll
;             for (int ds = 0; ds < NDS; ++ds) {
;                 s[0][kb] = __builtin_amdgcn_mfma_f32_16x16x32_bf16(kfr[kb][ds], qf[0][ds], ds == 0 ? cinit[0] : s[0][kb], 0, 0, 0);
;                 s[1][kb] = __builtin_amdgcn_mfma_f32_16x16x32_bf16(kfr[kb][ds], qf[1][ds], ds == 0 ? cinit[1] : s[1][kb], 0, 0, 0);
;             }
;         }
;         bf16x8 vf[4][2];
; #pragma unroll
;         for (int db = 0; db < 4; ++db)
; #pragma unroll
;             for (int G = 0; G < 2; ++G) {
;                 LAS unsigned char* vp = sb + voff + (32 * G * VSTR + 16 * db) * 2;
;                 const v4i16_t lo = __builtin_amdgcn_ds_read_tr16_b64_v4i16((LAS v4i16_t*)vp), hi = __builtin_amdgcn_ds_read_tr16_b64_v4i16((LAS v4i16_t*)(vp + 16 * VSTR * 2));
;                 vf[db][G] = (bf16x8){lo[0], lo[1], lo[2], lo[3], hi[0], hi[1], hi[2], hi[3]};
;             }
;         if (TY == 1) {
; #pragma unroll
;             for (int kb = 0; kb < 4; ++kb) {
;                 const f32x4 fk = *(const LAS f32x4*)(sb + KBYTES + VBYTES + (16 * kb + 4 * fq) * 4);
;                 s[0][kb] -= fk; s[1][kb] -= fk;
;             }
;         }
.LBB0_777:
	s_andn2_b64 vcc, exec, s[8:9]
	s_cbranch_vccnz .LBB0_762
	s_cmp_ge_u32 s24, s20
	s_cbranch_scc1 .LBB0_762
	s_min_i32 s8, s22, s20
	s_lshl_b32 s10, s8, 6
	s_mul_i32 s100, s10, s40
	s_mov_b32 s101, 0
	v_lshl_add_u64 v[10:11], s[100:101], 0, v[236:237]
	v_lshl_add_u64 v[12:13], s[100:101], 0, v[238:239]
	global_load_dwordx4 v[62:65], v[10:11], off
	global_load_dwordx4 v[66:69], v[12:13], off
	s_lshl_b32 s100, s10, 5
	v_lshl_add_u64 v[10:11], s[100:101], 0, v[240:241]
	global_load_dword v185, v[10:11], off
	s_sub_i32 s8, s23, 63
	s_cmp_gt_i32 s8, s21
	s_cbranch_scc1 .LBB0_787
	v_xor_b32_e32 v10, 0x80000000, v167
	v_xor_b32_e32 v14, 0x80000000, v166
	v_mov_b32_e32 v11, v10
	v_mov_b32_e32 v12, v10
	v_mov_b32_e32 v13, v10
	v_mov_b32_e32 v15, v14
	v_mov_b32_e32 v16, v14
	v_mov_b32_e32 v17, v14
	ds_read_b128 v[90:93], v186 offset:18688
	ds_read_b128 v[94:97], v186 offset:19712
	ds_read_b128 v[98:101], v186 offset:20736
	ds_read_b128 v[102:105], v186 offset:21760
	ds_read_b128 v[106:109], v186 offset:22784
	ds_read_b128 v[110:113], v186 offset:23808
	ds_read_b128 v[114:117], v186 offset:24832
	ds_read_b128 v[118:121], v186 offset:25856
	s_waitcnt lgkmcnt(7)
	v_mfma_f32_16x16x32_bf16 v[122:125], v[90:93], v[38:41], v[10:13]
	s_cmp_gt_i32 s23, s17
	s_mov_b64 s[8:9], -1
	v_mfma_f32_16x16x32_bf16 v[90:93], v[90:93], v[46:49], v[14:17]
	s_waitcnt lgkmcnt(6)
	v_mfma_f32_16x16x32_bf16 v[126:129], v[94:97], v[42:45], v[122:125]
	v_mfma_f32_16x16x32_bf16 v[130:133], v[94:97], v[50:53], v[90:93]
	s_waitcnt lgkmcnt(5)
	v_mfma_f32_16x16x32_bf16 v[90:93], v[98:101], v[38:41], v[10:13]
	v_mfma_f32_16x16x32_bf16 v[94:97], v[98:101], v[46:49], v[14:17]
	s_waitcnt lgkmcnt(4)
	v_mfma_f32_16x16x32_bf16 v[146:149], v[102:105], v[42:45], v[90:93]
	v_mfma_f32_16x16x32_bf16 v[190:193], v[102:105], v[50:53], v[94:97]
	s_waitcnt lgkmcnt(3)
	v_mfma_f32_16x16x32_bf16 v[90:93], v[106:109], v[38:41], v[10:13]
	v_mfma_f32_16x16x32_bf16 v[94:97], v[106:109], v[46:49], v[14:17]
	s_waitcnt lgkmcnt(1)
	v_mfma_f32_16x16x32_bf16 v[10:13], v[114:117], v[38:41], v[10:13]
	v_mfma_f32_16x16x32_bf16 v[14:17], v[114:117], v[46:49], v[14:17]
	v_mfma_f32_16x16x32_bf16 v[194:197], v[110:113], v[42:45], v[90:93]
	v_mfma_f32_16x16x32_bf16 v[122:125], v[110:113], v[50:53], v[94:97]
	s_waitcnt lgkmcnt(0)
	v_mfma_f32_16x16x32_bf16 v[140:143], v[118:121], v[42:45], v[10:13]
	v_mfma_f32_16x16x32_bf16 v[136:139], v[118:121], v[50:53], v[14:17]
	ds_read_b64_tr_b16 v[94:95], v187 offset:26880
	s_nop 0
	ds_read_b64_tr_b16 v[10:11], v187 offset:26912
	ds_read_b64_tr_b16 v[96:97], v187 offset:29440
	ds_read_b64_tr_b16 v[90:91], v187 offset:32000
	ds_read_b64_tr_b16 v[92:93], v187 offset:34560
	ds_read_b64_tr_b16 v[12:13], v187 offset:29472
	ds_read_b64_tr_b16 v[14:15], v187 offset:32032
	ds_read_b64_tr_b16 v[16:17], v187 offset:34592
	ds_read_b64_tr_b16 v[102:103], v187 offset:26944
	ds_read_b64_tr_b16 v[104:105], v187 offset:29504
	ds_read_b64_tr_b16 v[98:99], v187 offset:32064
	ds_read_b64_tr_b16 v[100:101], v187 offset:34624
	ds_read_b64_tr_b16 v[106:107], v187 offset:26976
	ds_read_b64_tr_b16 v[108:109], v187 offset:29536
	ds_read_b64_tr_b16 v[110:111], v187 offset:32096
	ds_read_b64_tr_b16 v[112:113], v187 offset:34656
	ds_read_b128 v[216:219], v188 offset:37120
	ds_read_b128 v[220:223], v188 offset:37184
	ds_read_b128 v[224:227], v188 offset:37248
	ds_read_b128 v[228:231], v188 offset:37312
	s_waitcnt lgkmcnt(0)
	s_cselect_b32 s99, 1, 0
	s_bitcmp1_b32 s41, 8
	s_cbranch_scc1 .Lfx_h1p1_end
	s_add_i32 s100, s22, -2
	s_cmp_ge_u32 s100, s20
	s_cbranch_scc1 .Lfx_h1p1_bar
	s_waitcnt vmcnt(5)
	ds_write_b128 v182, v[70:73]
	s_waitcnt vmcnt(4)
	ds_write_b128 v183, v[74:77] offset:8192
	s_and_saveexec_b64 s[100:101], s[4:5]
	s_cbranch_execz .Lfx_h1p1_w
	s_waitcnt vmcnt(3)
	ds_write_b32 v184, v189 offset:18432
